# P10 third round: each leftover unit shared by two workgroups, each running one 128-row half's MFMA blocks and stores; plus c11
# speedup vs baseline: 1.0015x; 1.0015x over previous
;     __host__ __device__ bool next(int i, Unit& u) const {
;         const long L = (long)i * G + c; if (L >= nwg) return false;
;         int wgid = (int)L; { const int q = nwg / NXCD, r = nwg % NXCD, xcd = wgid % NXCD, off = wgid / NXCD; wgid = (xcd < r ? xcd * (q + 1) : r * (q + 1) + (xcd - r) * q) + off; }
;         const int nig = WGM * nN, gid = wgid / nig, fm = gid * WGM, gsz = (nM - fm) < WGM ? (nM - fm) : WGM;
;         u.pm = fm + ((wgid % nig) % gsz); u.pn = (wgid % nig) / gsz; return true;
; template <class Epi, class Sched, bool ALIGN_EPI = false, bool SP2 = false>
; __device__ __forceinline__ void gemm_phase(PG8_LAS unsigned char* lds, const Gemm g, const Sched& S, const Epi& E) {
;     ...
;         const bool has_next = S.next(ui + 1, nxt);
.LBB0_2357:
	s_add_i32 s31, s31, 1
	s_mul_i32 s0, s31, s36
	s_mul_hi_u32 s1, s31, s66
	s_add_i32 s1, s1, s0
	s_mul_i32 s0, s31, s66
	s_add_u32 s0, s0, s74
	s_addc_u32 s1, s1, s37
	s_mov_b32 s98, 0
	s_cmpk_lg_i32 s66, 0x100
	s_cbranch_scc1 .Lp10s_a
	s_cmp_eq_u32 s31, 3
	s_cbranch_scc0 .Lp10s_b
	s_lshr_b32 s98, s74, 4
	s_and_b32 s98, s98, 1
	s_add_i32 s98, s98, 1
.Lp10s_b:
	s_cmp_eq_u32 s31, 2
	s_cbranch_scc0 .Lp10s_a
	s_cmp_gt_u32 s74, 31
	s_cbranch_scc1 .Lp10s_a
	s_and_b32 s0, s74, 15
	s_addk_i32 s0, 0x200
	s_mov_b32 s1, 0
.Lp10s_a:
	v_cmp_gt_i64_e32 vcc, s[0:1], v[144:145]
	v_cmp_lt_i64_e64 s[4:5], s[0:1], v[142:143]
	s_cbranch_vccnz .LBB0_2359
	s_ashr_i32 s1, s0, 31
	s_lshr_b32 s1, s1, 29
	s_add_i32 s1, s0, s1
	s_ashr_i32 s14, s1, 3
	s_and_b32 s1, s1, -8
	s_sub_i32 s0, s0, s1
	s_cmp_lt_i32 s0, 0
	s_cselect_b32 s1, s38, 0x42
	s_mul_i32 s0, s0, s1
	s_add_i32 s0, s0, s14
	s_ashr_i32 s1, s0, 31
	s_lshr_b32 s1, s1, 26
	s_add_i32 s1, s0, s1
	s_ashr_i32 s14, s1, 6
	s_lshl_b32 s14, s14, 3
	s_sub_i32 s15, 0x42, s14
	s_min_i32 s15, s15, 8
	s_abs_i32 s16, s15
	v_cvt_f32_u32_e32 v0, s16
	s_sub_i32 s43, 0, s16
	s_andn2_b32 s1, s1, 63
	s_sub_i32 s0, s0, s1
	v_rcp_iflag_f32_e32 v0, v0
	s_abs_i32 s1, s0
	s_xor_b32 s17, s0, s15
	s_ashr_i32 s17, s17, 31
	v_mul_f32_e32 v0, 0x4f7ffffe, v0
	v_cvt_u32_f32_e32 v0, v0
	s_nop 0
	v_readfirstlane_b32 s44, v0
	s_mul_i32 s43, s43, s44
	s_mul_hi_u32 s43, s44, s43
	s_add_i32 s44, s44, s43
	s_mul_hi_u32 s43, s1, s44
	s_mul_i32 s44, s43, s16
	s_sub_i32 s1, s1, s44
	s_add_i32 s47, s43, 1
	s_sub_i32 s44, s1, s16
	s_cmp_ge_u32 s1, s16
	s_cselect_b32 s43, s47, s43
	s_cselect_b32 s1, s44, s1
	s_add_i32 s44, s43, 1
	s_cmp_ge_u32 s1, s16
	s_cselect_b32 s1, s44, s43
	s_xor_b32 s1, s1, s17
	s_sub_i32 s43, s1, s17
	s_mul_i32 s1, s43, s15
	s_sub_i32 s0, s0, s1
	s_add_i32 s44, s14, s0

; #define PG8_STAGE(bufoff, gbase, voff) do { _Pragma("unroll") for (int _i = 0; _i < 2; ++_i) \
;         __builtin_amdgcn_global_load_lds((const unsigned*)((const char*)(gbase) + (voff)[_i]), (PG8_LAS unsigned*)(lds + (bufoff) + ldsw + _i * 8192), 16, 0, 0); } while (0)
; #define PG8_LDA(dst, b, h) do { _Pragma("unroll") for (int m = 0; m < 4; ++m) _Pragma("unroll") for (int k = 0; k < 2; ++k) dst[m][k] = *(const PG8_LAS bf16x8*)(lds + PG8_SA(b, h) + aoff + m * 2048 + k * 1024); } while (0)
; #define PG8_LDB(dst, b, h) do { _Pragma("unroll") for (int n = 0; n < 2; ++n) _Pragma("unroll") for (int k = 0; k < 2; ++k) dst[n][k] = *(const PG8_LAS bf16x8*)(lds + PG8_SB(b, h) + boff + n * 2048 + k * 1024); } while (0)
; #define PG8_MMA(ai, bj, At, Bt) do { __builtin_amdgcn_s_setprio(1); _Pragma("unroll") for (int m = 0; m < 4; ++m) _Pragma("unroll") for (int n = 0; n < 2; ++n) _Pragma("unroll") for (int k = 0; k < 2; ++k) \
;         acc[ai][bj][m][n] = __builtin_amdgcn_mfma_f32_16x16x32_bf16(Bt[n][k], At[m][k], acc[ai][bj][m][n], 0, 0, 0); __builtin_amdgcn_s_setprio(0); } while (0)
; #define PG8_WAIT_V(n) asm volatile("s_waitcnt vmcnt(" #n ")" ::: "memory")
; #define PG8_WAIT_L(n) asm volatile("s_waitcnt lgkmcnt(" #n ")" ::: "memory")
; #define PG8_BAR __builtin_amdgcn_s_barrier()
; #define PG8_SCHED __builtin_amdgcn_sched_barrier(0)
; template <class Epi, class Sched, bool ALIGN_EPI = false, bool SP2 = false>
; __device__ __forceinline__ void gemm_phase(PG8_LAS unsigned char* lds, const Gemm g, const Sched& S, const Epi& E) {
;     ...
;             PG8_LDB(B0, 0, 0); PG8_LDB(B1, 0, 1); PG8_SCHED; PG8_LDA(At, 0, 0); PG8_STAGE(PG8_SA(1, 1), a1 + hstepA, voffA);
;             PG8_WAIT_V(8); PG8_WAIT_L(0); PG8_BAR; PG8_MMA(0, 0, At, B0); PG8_MMA(0, 1, At, B1); PG8_BAR; PG8_SCHED;
;             PG8_LDA(At, 0, 1); PG8_STAGE(PG8_SB(0, 0), b2, voffB); PG8_STAGE(PG8_SB(0, 1), b2 + hstepB, voffB); PG8_STAGE(PG8_SA(0, 0), a2, voffA);
;             PG8_WAIT_V(8); PG8_WAIT_L(0); PG8_BAR; PG8_MMA(1, 0, At, B0); PG8_MMA(1, 1, At, B1); PG8_BAR; PG8_SCHED;
;             PG8_LDB(B0, 1, 0); PG8_LDB(B1, 1, 1); PG8_SCHED; PG8_LDA(At, 1, 0); PG8_STAGE(PG8_SA(0, 1), a2 + hstepA, voffA);
;             PG8_WAIT_V(8); PG8_WAIT_L(0); PG8_BAR; PG8_MMA(0, 0, At, B0); PG8_MMA(0, 1, At, B1); PG8_BAR; PG8_SCHED;
.LBB0_2364:
	ds_read_b128 v[146:149], v157
	ds_read_b128 v[150:153], v157 offset:1024
	ds_read_b128 v[160:163], v157 offset:2048
	ds_read_b128 v[164:167], v157 offset:3072
	ds_read_b128 v[168:171], v158
	ds_read_b128 v[172:175], v158 offset:1024
	ds_read_b128 v[176:179], v158 offset:2048
	ds_read_b128 v[180:183], v158 offset:3072
	s_add_u32 s18, s4, 0xffea0080
	s_addc_u32 s19, s5, -1
	s_cmpk_eq_i32 s49, 0x54
	s_cselect_b32 s21, s15, s19
	s_cselect_b32 s20, s14, s18
	s_cselect_b32 s19, s17, s48
	s_cselect_b32 s18, s16, s47
	v_lshl_add_u64 v[216:217], s[4:5], 0, v[138:139]
	s_add_i32 m0, s27, 0xc000
	ds_read_b128 v[184:187], v159
	ds_read_b128 v[188:191], v159 offset:1024
	ds_read_b128 v[192:195], v159 offset:2048
	ds_read_b128 v[196:199], v159 offset:3072
	ds_read_b128 v[200:203], v159 offset:4096
	ds_read_b128 v[204:207], v159 offset:5120
	ds_read_b128 v[208:211], v159 offset:6144
	ds_read_b128 v[212:215], v159 offset:7168
	global_load_lds_dwordx4 v[216:217], off
	v_lshl_add_u64 v[216:217], s[4:5], 0, v[140:141]
	s_add_i32 m0, s27, 0xe000
	s_nop 0
	global_load_lds_dwordx4 v[216:217], off
	s_waitcnt vmcnt(8)
	s_waitcnt lgkmcnt(0)
	s_barrier
	s_setprio 1
	s_waitcnt lgkmcnt(0)
	s_cmp_eq_u32 s98, 2
	s_cbranch_scc1 .Lp10s_k0
	v_mfma_f32_16x16x32_bf16 v[124:127], v[146:149], v[184:187], v[124:127]
	v_mfma_f32_16x16x32_bf16 v[120:123], v[160:163], v[184:187], v[120:123]
	v_mfma_f32_16x16x32_bf16 v[108:111], v[146:149], v[192:195], v[108:111]
	v_mfma_f32_16x16x32_bf16 v[104:107], v[160:163], v[192:195], v[104:107]
	v_mfma_f32_16x16x32_bf16 v[92:95], v[146:149], v[200:203], v[92:95]
	v_mfma_f32_16x16x32_bf16 v[88:91], v[160:163], v[200:203], v[88:91]
	v_mfma_f32_16x16x32_bf16 v[76:79], v[146:149], v[208:211], v[76:79]
	v_mfma_f32_16x16x32_bf16 v[72:75], v[160:163], v[208:211], v[72:75]
	v_mfma_f32_16x16x32_bf16 v[124:127], v[150:153], v[188:191], v[124:127]
	v_mfma_f32_16x16x32_bf16 v[120:123], v[164:167], v[188:191], v[120:123]
	v_mfma_f32_16x16x32_bf16 v[108:111], v[150:153], v[196:199], v[108:111]
	v_mfma_f32_16x16x32_bf16 v[104:107], v[164:167], v[196:199], v[104:107]
	v_mfma_f32_16x16x32_bf16 v[92:95], v[150:153], v[204:207], v[92:95]
	v_mfma_f32_16x16x32_bf16 v[88:91], v[164:167], v[204:207], v[88:91]
	v_mfma_f32_16x16x32_bf16 v[76:79], v[150:153], v[212:215], v[76:79]
	v_mfma_f32_16x16x32_bf16 v[72:75], v[164:167], v[212:215], v[72:75]
	s_setprio 0
	s_setprio 1
	v_mfma_f32_16x16x32_bf16 v[116:119], v[168:171], v[184:187], v[116:119]
	v_mfma_f32_16x16x32_bf16 v[112:115], v[176:179], v[184:187], v[112:115]
	v_mfma_f32_16x16x32_bf16 v[100:103], v[168:171], v[192:195], v[100:103]
	v_mfma_f32_16x16x32_bf16 v[96:99], v[176:179], v[192:195], v[96:99]
	v_mfma_f32_16x16x32_bf16 v[84:87], v[168:171], v[200:203], v[84:87]
	v_mfma_f32_16x16x32_bf16 v[80:83], v[176:179], v[200:203], v[80:83]
	v_mfma_f32_16x16x32_bf16 v[68:71], v[168:171], v[208:211], v[68:71]
	v_mfma_f32_16x16x32_bf16 v[64:67], v[176:179], v[208:211], v[64:67]
	v_mfma_f32_16x16x32_bf16 v[116:119], v[172:175], v[188:191], v[116:119]
	v_mfma_f32_16x16x32_bf16 v[112:115], v[180:183], v[188:191], v[112:115]
	v_mfma_f32_16x16x32_bf16 v[100:103], v[172:175], v[196:199], v[100:103]
	v_mfma_f32_16x16x32_bf16 v[96:99], v[180:183], v[196:199], v[96:99]
	v_mfma_f32_16x16x32_bf16 v[84:87], v[172:175], v[204:207], v[84:87]
	v_mfma_f32_16x16x32_bf16 v[80:83], v[180:183], v[204:207], v[80:83]
	v_mfma_f32_16x16x32_bf16 v[68:71], v[172:175], v[212:215], v[68:71]
	v_mfma_f32_16x16x32_bf16 v[64:67], v[180:183], v[212:215], v[64:67]
.Lp10s_k0:
	s_setprio 0
	s_barrier
	s_add_i32 s50, s39, s26
	v_lshl_add_u64 v[216:217], s[18:19], 0, v[132:133]
	s_mov_b32 m0, s50
	ds_read_b128 v[184:187], v159 offset:16384
	ds_read_b128 v[188:191], v159 offset:17408
	ds_read_b128 v[192:195], v159 offset:18432
	ds_read_b128 v[196:199], v159 offset:19456
	ds_read_b128 v[200:203], v159 offset:20480
	ds_read_b128 v[204:207], v159 offset:21504
	ds_read_b128 v[208:211], v159 offset:22528
	ds_read_b128 v[212:215], v159 offset:23552
	global_load_lds_dwordx4 v[216:217], off
	s_add_i32 m0, s50, 0x2000
	s_add_u32 s50, s18, 0x160000
	v_lshl_add_u64 v[218:219], s[18:19], 0, v[136:137]
	s_addc_u32 s51, s19, 0
	s_add_i32 s52, s40, s26
	global_load_lds_dwordx4 v[218:219], off
	v_lshl_add_u64 v[220:221], s[50:51], 0, v[132:133]
	s_mov_b32 m0, s52
	v_lshl_add_u64 v[222:223], s[20:21], 0, v[134:135]
	global_load_lds_dwordx4 v[220:221], off
	v_lshl_add_u64 v[220:221], s[50:51], 0, v[136:137]
	s_add_i32 m0, s52, 0x2000
	s_nop 0
	global_load_lds_dwordx4 v[220:221], off
	v_lshl_add_u64 v[220:221], s[20:21], 0, v[130:131]
	s_mov_b32 m0, s27
	s_nop 0
	global_load_lds_dwordx4 v[220:221], off
	s_mov_b32 m0, s28
	s_nop 0
	global_load_lds_dwordx4 v[222:223], off
	s_waitcnt vmcnt(8)
	s_waitcnt lgkmcnt(0)
	s_barrier
	s_setprio 1
	s_waitcnt lgkmcnt(0)
	s_cmp_eq_u32 s98, 1
	s_cbranch_scc1 .Lp10s_k1
; #define PG8_STAGE(bufoff, gbase, voff) do { _Pragma("unroll") for (int _i = 0; _i < 2; ++_i) \
;         __builtin_amdgcn_global_load_lds((const unsigned*)((const char*)(gbase) + (voff)[_i]), (PG8_LAS unsigned*)(lds + (bufoff) + ldsw + _i * 8192), 16, 0, 0); } while (0)
; #define PG8_LDA(dst, b, h) do { _Pragma("unroll") for (int m = 0; m < 4; ++m) _Pragma("unroll") for (int k = 0; k < 2; ++k) dst[m][k] = *(const PG8_LAS bf16x8*)(lds + PG8_SA(b, h) + aoff + m * 2048 + k * 1024); } while (0)
; #define PG8_LDB(dst, b, h) do { _Pragma("unroll") for (int n = 0; n < 2; ++n) _Pragma("unroll") for (int k = 0; k < 2; ++k) dst[n][k] = *(const PG8_LAS bf16x8*)(lds + PG8_SB(b, h) + boff + n * 2048 + k * 1024); } while (0)
; #define PG8_MMA(ai, bj, At, Bt) do { __builtin_amdgcn_s_setprio(1); _Pragma("unroll") for (int m = 0; m < 4; ++m) _Pragma("unroll") for (int n = 0; n < 2; ++n) _Pragma("unroll") for (int k = 0; k < 2; ++k) \
;         acc[ai][bj][m][n] = __builtin_amdgcn_mfma_f32_16x16x32_bf16(Bt[n][k], At[m][k], acc[ai][bj][m][n], 0, 0, 0); __builtin_amdgcn_s_setprio(0); } while (0)
; #define PG8_WAIT_V(n) asm volatile("s_waitcnt vmcnt(" #n ")" ::: "memory")
; #define PG8_WAIT_L(n) asm volatile("s_waitcnt lgkmcnt(" #n ")" ::: "memory")
; #define PG8_BAR __builtin_amdgcn_s_barrier()
; #define PG8_SCHED __builtin_amdgcn_sched_barrier(0)
; template <class Epi, class Sched, bool ALIGN_EPI = false, bool SP2 = false>
; __device__ __forceinline__ void gemm_phase(PG8_LAS unsigned char* lds, const Gemm g, const Sched& S, const Epi& E) {
;     ...
;             PG8_WAIT_V(8); PG8_WAIT_L(0); PG8_BAR; PG8_MMA(0, 0, At, B0); PG8_MMA(0, 1, At, B1); PG8_BAR; PG8_SCHED;
;             PG8_LDA(At, 0, 1); PG8_STAGE(PG8_SB(0, 0), b2, voffB); PG8_STAGE(PG8_SB(0, 1), b2 + hstepB, voffB); PG8_STAGE(PG8_SA(0, 0), a2, voffA);
;             PG8_WAIT_V(8); PG8_WAIT_L(0); PG8_BAR; PG8_MMA(1, 0, At, B0); PG8_MMA(1, 1, At, B1); PG8_BAR; PG8_SCHED;
;             PG8_LDB(B0, 1, 0); PG8_LDB(B1, 1, 1); PG8_SCHED; PG8_LDA(At, 1, 0); PG8_STAGE(PG8_SA(0, 1), a2 + hstepA, voffA);
;             PG8_WAIT_V(8); PG8_WAIT_L(0); PG8_BAR; PG8_MMA(0, 0, At, B0); PG8_MMA(0, 1, At, B1); PG8_BAR; PG8_SCHED;
	v_mfma_f32_16x16x32_bf16 v[60:63], v[146:149], v[184:187], v[60:63]
	v_mfma_f32_16x16x32_bf16 v[56:59], v[160:163], v[184:187], v[56:59]
	v_mfma_f32_16x16x32_bf16 v[44:47], v[146:149], v[192:195], v[44:47]
	v_mfma_f32_16x16x32_bf16 v[40:43], v[160:163], v[192:195], v[40:43]
	v_mfma_f32_16x16x32_bf16 v[28:31], v[146:149], v[200:203], v[28:31]
	v_mfma_f32_16x16x32_bf16 v[24:27], v[160:163], v[200:203], v[24:27]
	v_mfma_f32_16x16x32_bf16 v[12:15], v[146:149], v[208:211], v[12:15]
	v_mfma_f32_16x16x32_bf16 v[8:11], v[160:163], v[208:211], v[8:11]
	v_mfma_f32_16x16x32_bf16 v[60:63], v[150:153], v[188:191], v[60:63]
	v_mfma_f32_16x16x32_bf16 v[56:59], v[164:167], v[188:191], v[56:59]
	v_mfma_f32_16x16x32_bf16 v[44:47], v[150:153], v[196:199], v[44:47]
	v_mfma_f32_16x16x32_bf16 v[40:43], v[164:167], v[196:199], v[40:43]
	v_mfma_f32_16x16x32_bf16 v[28:31], v[150:153], v[204:207], v[28:31]
	v_mfma_f32_16x16x32_bf16 v[24:27], v[164:167], v[204:207], v[24:27]
	v_mfma_f32_16x16x32_bf16 v[12:15], v[150:153], v[212:215], v[12:15]
	v_mfma_f32_16x16x32_bf16 v[8:11], v[164:167], v[212:215], v[8:11]
	s_setprio 0
	s_setprio 1
	v_mfma_f32_16x16x32_bf16 v[52:55], v[168:171], v[184:187], v[52:55]
	v_mfma_f32_16x16x32_bf16 v[48:51], v[176:179], v[184:187], v[48:51]
	v_mfma_f32_16x16x32_bf16 v[36:39], v[168:171], v[192:195], v[36:39]
	v_mfma_f32_16x16x32_bf16 v[32:35], v[176:179], v[192:195], v[32:35]
	v_mfma_f32_16x16x32_bf16 v[20:23], v[168:171], v[200:203], v[20:23]
	v_mfma_f32_16x16x32_bf16 v[16:19], v[176:179], v[200:203], v[16:19]
	v_mfma_f32_16x16x32_bf16 v[4:7], v[168:171], v[208:211], v[4:7]
	v_mfma_f32_16x16x32_bf16 v[0:3], v[176:179], v[208:211], v[0:3]
	v_mfma_f32_16x16x32_bf16 v[52:55], v[172:175], v[188:191], v[52:55]
	v_mfma_f32_16x16x32_bf16 v[48:51], v[180:183], v[188:191], v[48:51]
	v_mfma_f32_16x16x32_bf16 v[36:39], v[172:175], v[196:199], v[36:39]
	v_mfma_f32_16x16x32_bf16 v[32:35], v[180:183], v[196:199], v[32:35]
	v_mfma_f32_16x16x32_bf16 v[20:23], v[172:175], v[204:207], v[20:23]
	v_mfma_f32_16x16x32_bf16 v[16:19], v[180:183], v[204:207], v[16:19]
	v_mfma_f32_16x16x32_bf16 v[4:7], v[172:175], v[212:215], v[4:7]
	v_mfma_f32_16x16x32_bf16 v[0:3], v[180:183], v[212:215], v[0:3]
.Lp10s_k1:
	s_setprio 0
	s_barrier
	s_add_i32 s50, 0, 0x18000
	v_add_u32_e32 v128, s50, v155
	s_add_i32 s51, 0, 0x1c000
	ds_read_b128 v[146:149], v128
	ds_read_b128 v[150:153], v128 offset:1024
	ds_read_b128 v[160:163], v128 offset:2048
	ds_read_b128 v[164:167], v128 offset:3072
	v_add_u32_e32 v128, s51, v155
	ds_read_b128 v[168:171], v128
	ds_read_b128 v[172:175], v128 offset:1024
	ds_read_b128 v[176:179], v128 offset:2048
	ds_read_b128 v[180:183], v128 offset:3072
	s_add_u32 s20, s20, 0x160000
	s_addc_u32 s21, s21, 0
	s_mov_b32 m0, s29
	v_lshl_add_u64 v[224:225], s[20:21], 0, v[130:131]
	ds_read_b128 v[184:187], v159 offset:32768
	ds_read_b128 v[188:191], v159 offset:33792
	ds_read_b128 v[192:195], v159 offset:34816
	ds_read_b128 v[196:199], v159 offset:35840
	ds_read_b128 v[200:203], v159 offset:36864
	ds_read_b128 v[204:207], v159 offset:37888
	ds_read_b128 v[208:211], v159 offset:38912
	ds_read_b128 v[212:215], v159 offset:39936
	global_load_lds_dwordx4 v[224:225], off
	v_lshl_add_u64 v[224:225], s[20:21], 0, v[134:135]
	s_mov_b32 m0, s30
	s_nop 0
	global_load_lds_dwordx4 v[224:225], off
	s_waitcnt vmcnt(8)
	s_waitcnt lgkmcnt(0)
	s_barrier
	s_setprio 1
	s_waitcnt lgkmcnt(0)
	s_cmp_eq_u32 s98, 2
	s_cbranch_scc1 .Lp10s_k2
	v_mfma_f32_16x16x32_bf16 v[124:127], v[146:149], v[184:187], v[124:127]
	v_mfma_f32_16x16x32_bf16 v[120:123], v[160:163], v[184:187], v[120:123]
	v_mfma_f32_16x16x32_bf16 v[108:111], v[146:149], v[192:195], v[108:111]
	v_mfma_f32_16x16x32_bf16 v[104:107], v[160:163], v[192:195], v[104:107]
	v_mfma_f32_16x16x32_bf16 v[92:95], v[146:149], v[200:203], v[92:95]
	v_mfma_f32_16x16x32_bf16 v[88:91], v[160:163], v[200:203], v[88:91]
	v_mfma_f32_16x16x32_bf16 v[76:79], v[146:149], v[208:211], v[76:79]
	v_mfma_f32_16x16x32_bf16 v[72:75], v[160:163], v[208:211], v[72:75]
	v_mfma_f32_16x16x32_bf16 v[124:127], v[150:153], v[188:191], v[124:127]
	v_mfma_f32_16x16x32_bf16 v[120:123], v[164:167], v[188:191], v[120:123]
	v_mfma_f32_16x16x32_bf16 v[108:111], v[150:153], v[196:199], v[108:111]
	v_mfma_f32_16x16x32_bf16 v[104:107], v[164:167], v[196:199], v[104:107]
	v_mfma_f32_16x16x32_bf16 v[92:95], v[150:153], v[204:207], v[92:95]
	v_mfma_f32_16x16x32_bf16 v[88:91], v[164:167], v[204:207], v[88:91]
	v_mfma_f32_16x16x32_bf16 v[76:79], v[150:153], v[212:215], v[76:79]
	v_mfma_f32_16x16x32_bf16 v[72:75], v[164:167], v[212:215], v[72:75]
	s_setprio 0
	s_setprio 1
	v_mfma_f32_16x16x32_bf16 v[116:119], v[168:171], v[184:187], v[116:119]
	v_mfma_f32_16x16x32_bf16 v[112:115], v[176:179], v[184:187], v[112:115]
	v_mfma_f32_16x16x32_bf16 v[100:103], v[168:171], v[192:195], v[100:103]
	v_mfma_f32_16x16x32_bf16 v[96:99], v[176:179], v[192:195], v[96:99]
	v_mfma_f32_16x16x32_bf16 v[84:87], v[168:171], v[200:203], v[84:87]
	v_mfma_f32_16x16x32_bf16 v[80:83], v[176:179], v[200:203], v[80:83]
	v_mfma_f32_16x16x32_bf16 v[68:71], v[168:171], v[208:211], v[68:71]
	v_mfma_f32_16x16x32_bf16 v[64:67], v[176:179], v[208:211], v[64:67]
	v_mfma_f32_16x16x32_bf16 v[116:119], v[172:175], v[188:191], v[116:119]
	v_mfma_f32_16x16x32_bf16 v[112:115], v[180:183], v[188:191], v[112:115]
	v_mfma_f32_16x16x32_bf16 v[100:103], v[172:175], v[196:199], v[100:103]
	v_mfma_f32_16x16x32_bf16 v[96:99], v[180:183], v[196:199], v[96:99]
	v_mfma_f32_16x16x32_bf16 v[84:87], v[172:175], v[204:207], v[84:87]
	v_mfma_f32_16x16x32_bf16 v[80:83], v[180:183], v[204:207], v[80:83]
	v_mfma_f32_16x16x32_bf16 v[68:71], v[172:175], v[212:215], v[68:71]
	v_mfma_f32_16x16x32_bf16 v[64:67], v[180:183], v[212:215], v[64:67]
; #define PG8_STAGE(bufoff, gbase, voff) do { _Pragma("unroll") for (int _i = 0; _i < 2; ++_i) \
;         __builtin_amdgcn_global_load_lds((const unsigned*)((const char*)(gbase) + (voff)[_i]), (PG8_LAS unsigned*)(lds + (bufoff) + ldsw + _i * 8192), 16, 0, 0); } while (0)
; #define PG8_LDA(dst, b, h) do { _Pragma("unroll") for (int m = 0; m < 4; ++m) _Pragma("unroll") for (int k = 0; k < 2; ++k) dst[m][k] = *(const PG8_LAS bf16x8*)(lds + PG8_SA(b, h) + aoff + m * 2048 + k * 1024); } while (0)
; #define PG8_WAIT_V(n) asm volatile("s_waitcnt vmcnt(" #n ")" ::: "memory")
; #define PG8_BAR __builtin_amdgcn_s_barrier()
; template <class Epi, class Sched, bool ALIGN_EPI = false, bool SP2 = false>
; __device__ __forceinline__ void gemm_phase(PG8_LAS unsigned char* lds, const Gemm g, const Sched& S, const Epi& E) {
;     ...
;             PG8_WAIT_V(8); PG8_WAIT_L(0); PG8_BAR; PG8_MMA(0, 0, At, B0); PG8_MMA(0, 1, At, B1); PG8_BAR; PG8_SCHED;
;             PG8_LDA(At, 1, 1); PG8_STAGE(PG8_SB(1, 0), b3, voffB); PG8_STAGE(PG8_SB(1, 1), b3 + hstepB, voffB); PG8_STAGE(PG8_SA(1, 0), a3, voffA);
;             PG8_WAIT_V(8); PG8_WAIT_L(0); PG8_BAR; PG8_MMA(1, 0, At, B0); PG8_MMA(1, 1, At, B1); PG8_BAR; PG8_SCHED;
;     ...
;         if constexpr (ALIGN_EPI) { if (wr == 0) PG8_BAR; }
;         if constexpr (!Epi::AFTER_DRAIN) { E(acc, cur, wr, wc, fr, fq); S.done(cur); }
;     __device__ __forceinline__ void operator()(const f32x4 (&acc)[2][2][4][2], const pg8::Unit& u, int wr, int wc, int fr, int fq) const {
;         const int col0 = u.pn * 256 + wc * 32 + 8 * fq;
; #pragma unroll
;         for (int ai = 0; ai < 2; ++ai)
; #pragma unroll
;             for (int m = 0; m < 4; ++m) {
;                 const int row = u.pm * 256 + ai * 128 + wr * 64 + m * 16 + fr;
;                 const int b = row < TP ? 0 : 1 + ((row - TP) >> 6);
;                 const float* sp = (row < TP ? srcP + (size_t)row * DM : srcS + (size_t)(row - TP) * DM) + col0;
;                 const float* gp = gate + (size_t)b * MODW + col0; float* dp = dst + (size_t)row * DM + col0;
; #pragma unroll
;                 for (int bj = 0; bj < 2; ++bj)
; #pragma unroll
;                     for (int n = 0; n < 2; ++n) { const f32x4 x = *(const f32x4*)(sp + bj * 128 + 4 * n), gg = *(const f32x4*)(gp + bj * 128 + 4 * n);
;                         *(f32x4*)(dp + bj * 128 + 4 * n) = x + gg * acc[ai][bj][m][n]; }
.Lp10s_k2:
	s_setprio 0
	s_barrier
	s_add_i32 s20, s50, s26
	v_lshl_add_u64 v[216:217], v[216:217], 0, s[10:11]
	s_mov_b32 m0, s20
	ds_read_b128 v[184:187], v159 offset:49152
	ds_read_b128 v[188:191], v159 offset:50176
	ds_read_b128 v[192:195], v159 offset:51200
	ds_read_b128 v[196:199], v159 offset:52224
	ds_read_b128 v[200:203], v159 offset:53248
	ds_read_b128 v[204:207], v159 offset:54272
	ds_read_b128 v[208:211], v159 offset:55296
	ds_read_b128 v[212:215], v159 offset:56320
	global_load_lds_dwordx4 v[216:217], off
	s_add_i32 m0, s20, 0x2000
	s_add_u32 s18, s18, 0x160080
	v_lshl_add_u64 v[216:217], v[218:219], 0, s[10:11]
	s_addc_u32 s19, s19, 0
	s_add_i32 s20, s51, s26
	global_load_lds_dwordx4 v[216:217], off
	v_lshl_add_u64 v[216:217], s[18:19], 0, v[132:133]
	s_mov_b32 m0, s20
	s_nop 0
	global_load_lds_dwordx4 v[216:217], off
	v_lshl_add_u64 v[216:217], s[18:19], 0, v[136:137]
	s_add_i32 m0, s20, 0x2000
	s_nop 0
	global_load_lds_dwordx4 v[216:217], off
	v_lshl_add_u64 v[216:217], v[220:221], 0, s[10:11]
	s_mov_b32 m0, s34
	s_nop 0
	global_load_lds_dwordx4 v[216:217], off
	v_lshl_add_u64 v[216:217], v[222:223], 0, s[10:11]
	s_mov_b32 m0, s35
	s_nop 0
	global_load_lds_dwordx4 v[216:217], off
	s_waitcnt vmcnt(8)
	s_waitcnt lgkmcnt(0)
	s_barrier
	s_setprio 1
	s_waitcnt lgkmcnt(0)
	s_cmp_eq_u32 s98, 1
	s_cbranch_scc1 .Lp10s_k3
	v_mfma_f32_16x16x32_bf16 v[60:63], v[146:149], v[184:187], v[60:63]
	v_mfma_f32_16x16x32_bf16 v[56:59], v[160:163], v[184:187], v[56:59]
	v_mfma_f32_16x16x32_bf16 v[44:47], v[146:149], v[192:195], v[44:47]
	v_mfma_f32_16x16x32_bf16 v[40:43], v[160:163], v[192:195], v[40:43]
	v_mfma_f32_16x16x32_bf16 v[28:31], v[146:149], v[200:203], v[28:31]
	v_mfma_f32_16x16x32_bf16 v[24:27], v[160:163], v[200:203], v[24:27]
	v_mfma_f32_16x16x32_bf16 v[12:15], v[146:149], v[208:211], v[12:15]
	v_mfma_f32_16x16x32_bf16 v[8:11], v[160:163], v[208:211], v[8:11]
	v_mfma_f32_16x16x32_bf16 v[60:63], v[150:153], v[188:191], v[60:63]
	v_mfma_f32_16x16x32_bf16 v[56:59], v[164:167], v[188:191], v[56:59]
	v_mfma_f32_16x16x32_bf16 v[44:47], v[150:153], v[196:199], v[44:47]
	v_mfma_f32_16x16x32_bf16 v[40:43], v[164:167], v[196:199], v[40:43]
	v_mfma_f32_16x16x32_bf16 v[28:31], v[150:153], v[204:207], v[28:31]
	v_mfma_f32_16x16x32_bf16 v[24:27], v[164:167], v[204:207], v[24:27]
	v_mfma_f32_16x16x32_bf16 v[12:15], v[150:153], v[212:215], v[12:15]
	v_mfma_f32_16x16x32_bf16 v[8:11], v[164:167], v[212:215], v[8:11]
	s_setprio 0
	s_setprio 1
	v_mfma_f32_16x16x32_bf16 v[52:55], v[168:171], v[184:187], v[52:55]
	v_mfma_f32_16x16x32_bf16 v[48:51], v[176:179], v[184:187], v[48:51]
	v_mfma_f32_16x16x32_bf16 v[36:39], v[168:171], v[192:195], v[36:39]
	v_mfma_f32_16x16x32_bf16 v[32:35], v[176:179], v[192:195], v[32:35]
	v_mfma_f32_16x16x32_bf16 v[20:23], v[168:171], v[200:203], v[20:23]
	v_mfma_f32_16x16x32_bf16 v[16:19], v[176:179], v[200:203], v[16:19]
	v_mfma_f32_16x16x32_bf16 v[4:7], v[168:171], v[208:211], v[4:7]
	v_mfma_f32_16x16x32_bf16 v[0:3], v[176:179], v[208:211], v[0:3]
	v_mfma_f32_16x16x32_bf16 v[52:55], v[172:175], v[188:191], v[52:55]
	v_mfma_f32_16x16x32_bf16 v[48:51], v[180:183], v[188:191], v[48:51]
	v_mfma_f32_16x16x32_bf16 v[36:39], v[172:175], v[196:199], v[36:39]
	v_mfma_f32_16x16x32_bf16 v[32:35], v[180:183], v[196:199], v[32:35]
	v_mfma_f32_16x16x32_bf16 v[20:23], v[172:175], v[204:207], v[20:23]
	v_mfma_f32_16x16x32_bf16 v[16:19], v[180:183], v[204:207], v[16:19]
	v_mfma_f32_16x16x32_bf16 v[4:7], v[172:175], v[212:215], v[4:7]
	v_mfma_f32_16x16x32_bf16 v[0:3], v[180:183], v[212:215], v[0:3]
.Lp10s_k3:
	s_setprio 0
	s_barrier
	s_add_i32 s49, s49, 2
	s_add_u32 s4, s4, 0x100
	s_addc_u32 s5, s5, 0
	s_add_u32 s47, s47, 0x100
	s_addc_u32 s48, s48, 0
	s_cmpk_gt_u32 s49, 0x55
	s_cbranch_scc0 .LBB0_2364
	s_and_b64 vcc, exec, s[12:13]
	s_cbranch_vccz .LBB0_2367
	s_barrier
.LBB0_2367:
	v_lshl_add_u32 v148, s46, 8, v154
	v_cmp_gt_i32_e32 vcc, s33, v148
	v_cmp_lt_i32_e64 s[4:5], s42, v148
	v_add_u32_e32 v128, 0xffffc000, v148
	s_and_saveexec_b64 s[18:19], s[4:5]
	s_xor_b64 s[4:5], exec, s[18:19]
	v_lshlrev_b64 v[146:147], 13, v[128:129]
	v_mov_b32_e32 v149, v129
	v_lshl_add_u64 v[152:153], s[6:7], 0, v[146:147]
	v_lshlrev_b64 v[150:151], 13, v[148:149]
	s_andn2_saveexec_b64 s[4:5], s[4:5]
	v_ashrrev_i32_e32 v149, 31, v148
	v_lshlrev_b64 v[150:151], 13, v[148:149]
	v_lshl_add_u64 v[152:153], s[60:61], 0, v[150:151]
	s_or_b64 exec, exec, s[4:5]
	v_lshl_or_b32 v146, s45, 8, v156
	v_ashrrev_i32_e32 v147, 31, v146
	v_lshrrev_b32_e32 v128, 6, v128
	v_add_u32_e32 v128, 1, v128
	v_lshlrev_b64 v[146:147], 2, v[146:147]
	v_cndmask_b32_e64 v128, v128, 0, vcc
	v_lshl_add_u64 v[168:169], v[152:153], 0, v[146:147]
	v_mov_b64_e32 v[152:153], s[8:9]
	v_mad_u64_u32 v[152:153], s[4:5], v128, s41, v[152:153]
	v_lshl_add_u64 v[170:171], v[152:153], 0, v[146:147]
	global_load_dwordx4 v[176:179], v[168:169], off
	global_load_dwordx4 v[180:183], v[170:171], off
	global_load_dwordx4 v[184:187], v[168:169], off offset:16
	global_load_dwordx4 v[188:191], v[170:171], off offset:16
	global_load_dwordx4 v[192:195], v[168:169], off offset:512
	global_load_dwordx4 v[196:199], v[170:171], off offset:512
	global_load_dwordx4 v[200:203], v[168:169], off offset:528
	global_load_dwordx4 v[204:207], v[170:171], off offset:528
	v_lshl_add_u64 v[150:151], s[60:61], 0, v[150:151]
	v_lshl_add_u64 v[172:173], v[150:151], 0, v[146:147]
	v_add_u32_e32 v128, 0xffffc010, v148
	s_waitcnt vmcnt(0)
;     __device__ __forceinline__ void operator()(const f32x4 (&acc)[2][2][4][2], const pg8::Unit& u, int wr, int wc, int fr, int fq) const {
;         const int col0 = u.pn * 256 + wc * 32 + 8 * fq;
; #pragma unroll
;         for (int ai = 0; ai < 2; ++ai)
; #pragma unroll
;             for (int m = 0; m < 4; ++m) {
;                 const int row = u.pm * 256 + ai * 128 + wr * 64 + m * 16 + fr;
;                 const int b = row < TP ? 0 : 1 + ((row - TP) >> 6);
;                 const float* sp = (row < TP ? srcP + (size_t)row * DM : srcS + (size_t)(row - TP) * DM) + col0;
;                 const float* gp = gate + (size_t)b * MODW + col0; float* dp = dst + (size_t)row * DM + col0;
; #pragma unroll
;                 for (int bj = 0; bj < 2; ++bj)
; #pragma unroll
;                     for (int n = 0; n < 2; ++n) { const f32x4 x = *(const f32x4*)(sp + bj * 128 + 4 * n), gg = *(const f32x4*)(gp + bj * 128 + 4 * n);
;                         *(f32x4*)(dp + bj * 128 + 4 * n) = x + gg * acc[ai][bj][m][n]; }
	v_pk_fma_f32 v[126:127], v[126:127], v[182:183], v[178:179]
	v_pk_fma_f32 v[124:125], v[124:125], v[180:181], v[176:177]
	s_cmp_eq_u32 s98, 2
	s_cselect_b64 s[100:101], 0, -1
	s_mov_b64 exec, s[100:101]
	global_store_dwordx4 v[172:173], v[124:127], off
	s_mov_b64 exec, -1
	s_nop 1
	s_nop 0
	v_pk_fma_f32 v[122:123], v[122:123], v[190:191], v[186:187]
	v_pk_fma_f32 v[120:121], v[120:121], v[188:189], v[184:185]
	s_mov_b64 exec, s[100:101]
	global_store_dwordx4 v[172:173], v[120:123], off offset:16
	s_mov_b64 exec, -1
	s_nop 1
	s_nop 0
	v_pk_fma_f32 v[118:119], v[118:119], v[198:199], v[194:195]
	v_pk_fma_f32 v[116:117], v[116:117], v[196:197], v[192:193]
	s_mov_b64 exec, s[100:101]
	global_store_dwordx4 v[172:173], v[116:119], off offset:512
	s_mov_b64 exec, -1
	s_nop 1
	v_or_b32_e32 v116, 16, v148
	v_cmp_gt_i32_e32 vcc, s33, v116
	v_cmp_lt_i32_e64 s[4:5], s42, v116
	s_nop 0
	v_pk_fma_f32 v[114:115], v[114:115], v[206:207], v[202:203]
	v_pk_fma_f32 v[112:113], v[112:113], v[204:205], v[200:201]
	s_mov_b64 exec, s[100:101]
	global_store_dwordx4 v[172:173], v[112:115], off offset:528
	s_mov_b64 exec, -1
	s_and_saveexec_b64 s[18:19], s[4:5]
	s_xor_b64 s[4:5], exec, s[18:19]
	v_lshlrev_b64 v[112:113], 13, v[128:129]
	v_mov_b32_e32 v117, v129
	v_lshl_add_u64 v[114:115], s[6:7], 0, v[112:113]
	v_lshlrev_b64 v[112:113], 13, v[116:117]
	s_andn2_saveexec_b64 s[4:5], s[4:5]
	v_ashrrev_i32_e32 v117, 31, v116
	v_lshlrev_b64 v[112:113], 13, v[116:117]
	v_lshl_add_u64 v[114:115], s[60:61], 0, v[112:113]
	s_or_b64 exec, exec, s[4:5]
	v_lshrrev_b32_e32 v116, 6, v128
	v_add_u32_e32 v116, 1, v116
	v_cndmask_b32_e64 v116, v116, 0, vcc
	v_lshl_add_u64 v[122:123], v[114:115], 0, v[146:147]
	v_mov_b64_e32 v[114:115], s[8:9]
	v_mad_u64_u32 v[114:115], s[4:5], v116, s41, v[114:115]
	v_lshl_add_u64 v[124:125], v[114:115], 0, v[146:147]
	global_load_dwordx4 v[176:179], v[122:123], off
	global_load_dwordx4 v[180:183], v[124:125], off
	global_load_dwordx4 v[184:187], v[122:123], off offset:16
	global_load_dwordx4 v[188:191], v[124:125], off offset:16
	global_load_dwordx4 v[192:195], v[122:123], off offset:512
	global_load_dwordx4 v[196:199], v[124:125], off offset:512
	global_load_dwordx4 v[200:203], v[122:123], off offset:528
	global_load_dwordx4 v[204:207], v[124:125], off offset:528
	v_lshl_add_u64 v[112:113], s[60:61], 0, v[112:113]
	v_lshl_add_u64 v[126:127], v[112:113], 0, v[146:147]
	v_add_u32_e32 v128, 0xffffc020, v148
	s_waitcnt vmcnt(0)
	v_pk_fma_f32 v[110:111], v[110:111], v[182:183], v[178:179]
	v_pk_fma_f32 v[108:109], v[108:109], v[180:181], v[176:177]
	s_mov_b64 exec, s[100:101]
	global_store_dwordx4 v[126:127], v[108:111], off
	s_mov_b64 exec, -1
	s_nop 1
	s_nop 0
	v_pk_fma_f32 v[106:107], v[106:107], v[190:191], v[186:187]
	v_pk_fma_f32 v[104:105], v[104:105], v[188:189], v[184:185]
	s_mov_b64 exec, s[100:101]
	global_store_dwordx4 v[126:127], v[104:107], off offset:16
	s_mov_b64 exec, -1
	s_nop 1
	s_nop 0
	v_pk_fma_f32 v[102:103], v[102:103], v[198:199], v[194:195]
	v_pk_fma_f32 v[100:101], v[100:101], v[196:197], v[192:193]
	s_mov_b64 exec, s[100:101]
	global_store_dwordx4 v[126:127], v[100:103], off offset:512
	s_mov_b64 exec, -1
	s_nop 1
	v_or_b32_e32 v100, 32, v148
	v_cmp_gt_i32_e32 vcc, s33, v100
	v_cmp_lt_i32_e64 s[4:5], s42, v100
	s_nop 0
	v_pk_fma_f32 v[98:99], v[98:99], v[206:207], v[202:203]
	v_pk_fma_f32 v[96:97], v[96:97], v[204:205], v[200:201]
	s_mov_b64 exec, s[100:101]
	global_store_dwordx4 v[126:127], v[96:99], off offset:528
	s_mov_b64 exec, -1
	s_and_saveexec_b64 s[18:19], s[4:5]
	s_xor_b64 s[4:5], exec, s[18:19]
	v_lshlrev_b64 v[96:97], 13, v[128:129]
	v_mov_b32_e32 v101, v129
	v_lshl_add_u64 v[98:99], s[6:7], 0, v[96:97]
	v_lshlrev_b64 v[96:97], 13, v[100:101]
	s_andn2_saveexec_b64 s[4:5], s[4:5]
	v_ashrrev_i32_e32 v101, 31, v100
	v_lshlrev_b64 v[96:97], 13, v[100:101]
	v_lshl_add_u64 v[98:99], s[60:61], 0, v[96:97]
	s_or_b64 exec, exec, s[4:5]
	v_lshrrev_b32_e32 v100, 6, v128
	v_add_u32_e32 v100, 1, v100
	v_cndmask_b32_e64 v100, v100, 0, vcc
	v_lshl_add_u64 v[106:107], v[98:99], 0, v[146:147]
	v_mov_b64_e32 v[98:99], s[8:9]
	v_mad_u64_u32 v[98:99], s[4:5], v100, s41, v[98:99]
	v_lshl_add_u64 v[108:109], v[98:99], 0, v[146:147]
	global_load_dwordx4 v[176:179], v[106:107], off
	global_load_dwordx4 v[180:183], v[108:109], off
	global_load_dwordx4 v[184:187], v[106:107], off offset:16
	global_load_dwordx4 v[188:191], v[108:109], off offset:16
	global_load_dwordx4 v[192:195], v[106:107], off offset:512
	global_load_dwordx4 v[196:199], v[108:109], off offset:512
	global_load_dwordx4 v[200:203], v[106:107], off offset:528
	global_load_dwordx4 v[204:207], v[108:109], off offset:528
	v_lshl_add_u64 v[96:97], s[60:61], 0, v[96:97]
	v_lshl_add_u64 v[110:111], v[96:97], 0, v[146:147]
	v_add_u32_e32 v128, 0xffffc030, v148
	s_waitcnt vmcnt(0)
;     __device__ __forceinline__ void operator()(const f32x4 (&acc)[2][2][4][2], const pg8::Unit& u, int wr, int wc, int fr, int fq) const {
;         const int col0 = u.pn * 256 + wc * 32 + 8 * fq;
; #pragma unroll
;         for (int ai = 0; ai < 2; ++ai)
; #pragma unroll
;             for (int m = 0; m < 4; ++m) {
;                 const int row = u.pm * 256 + ai * 128 + wr * 64 + m * 16 + fr;
;                 const int b = row < TP ? 0 : 1 + ((row - TP) >> 6);
;                 const float* sp = (row < TP ? srcP + (size_t)row * DM : srcS + (size_t)(row - TP) * DM) + col0;
;                 const float* gp = gate + (size_t)b * MODW + col0; float* dp = dst + (size_t)row * DM + col0;
; #pragma unroll
;                 for (int bj = 0; bj < 2; ++bj)
; #pragma unroll
;                     for (int n = 0; n < 2; ++n) { const f32x4 x = *(const f32x4*)(sp + bj * 128 + 4 * n), gg = *(const f32x4*)(gp + bj * 128 + 4 * n);
;                         *(f32x4*)(dp + bj * 128 + 4 * n) = x + gg * acc[ai][bj][m][n]; }
	v_pk_fma_f32 v[94:95], v[94:95], v[182:183], v[178:179]
	v_pk_fma_f32 v[92:93], v[92:93], v[180:181], v[176:177]
	s_mov_b64 exec, s[100:101]
	global_store_dwordx4 v[110:111], v[92:95], off
	s_mov_b64 exec, -1
	s_nop 1
	s_nop 0
	v_pk_fma_f32 v[90:91], v[90:91], v[190:191], v[186:187]
	v_pk_fma_f32 v[88:89], v[88:89], v[188:189], v[184:185]
	s_mov_b64 exec, s[100:101]
	global_store_dwordx4 v[110:111], v[88:91], off offset:16
	s_mov_b64 exec, -1
	s_nop 1
	s_nop 0
	v_pk_fma_f32 v[86:87], v[86:87], v[198:199], v[194:195]
	v_pk_fma_f32 v[84:85], v[84:85], v[196:197], v[192:193]
	s_mov_b64 exec, s[100:101]
	global_store_dwordx4 v[110:111], v[84:87], off offset:512
	s_mov_b64 exec, -1
	s_nop 1
	v_or_b32_e32 v84, 48, v148
	v_cmp_gt_i32_e32 vcc, s33, v84
	v_cmp_lt_i32_e64 s[4:5], s42, v84
	s_nop 0
	v_pk_fma_f32 v[82:83], v[82:83], v[206:207], v[202:203]
	v_pk_fma_f32 v[80:81], v[80:81], v[204:205], v[200:201]
	s_mov_b64 exec, s[100:101]
	global_store_dwordx4 v[110:111], v[80:83], off offset:528
	s_mov_b64 exec, -1
	s_and_saveexec_b64 s[18:19], s[4:5]
	s_xor_b64 s[4:5], exec, s[18:19]
	v_lshlrev_b64 v[80:81], 13, v[128:129]
	v_mov_b32_e32 v85, v129
	v_lshl_add_u64 v[82:83], s[6:7], 0, v[80:81]
	v_lshlrev_b64 v[80:81], 13, v[84:85]
	s_andn2_saveexec_b64 s[4:5], s[4:5]
	v_ashrrev_i32_e32 v85, 31, v84
	v_lshlrev_b64 v[80:81], 13, v[84:85]
	v_lshl_add_u64 v[82:83], s[60:61], 0, v[80:81]
	s_or_b64 exec, exec, s[4:5]
	v_lshrrev_b32_e32 v84, 6, v128
	v_add_u32_e32 v84, 1, v84
	v_cndmask_b32_e64 v84, v84, 0, vcc
	v_lshl_add_u64 v[90:91], v[82:83], 0, v[146:147]
	v_mov_b64_e32 v[82:83], s[8:9]
	v_mad_u64_u32 v[82:83], s[4:5], v84, s41, v[82:83]
	v_lshl_add_u64 v[92:93], v[82:83], 0, v[146:147]
	global_load_dwordx4 v[176:179], v[90:91], off
	global_load_dwordx4 v[180:183], v[92:93], off
	global_load_dwordx4 v[184:187], v[90:91], off offset:16
	global_load_dwordx4 v[188:191], v[92:93], off offset:16
	global_load_dwordx4 v[192:195], v[90:91], off offset:512
	global_load_dwordx4 v[196:199], v[92:93], off offset:512
	global_load_dwordx4 v[200:203], v[90:91], off offset:528
	global_load_dwordx4 v[204:207], v[92:93], off offset:528
	v_lshl_add_u64 v[80:81], s[60:61], 0, v[80:81]
	v_lshl_add_u64 v[94:95], v[80:81], 0, v[146:147]
	v_add_u32_e32 v128, 0xffffc080, v148
	s_waitcnt vmcnt(0)
	v_pk_fma_f32 v[78:79], v[78:79], v[182:183], v[178:179]
	v_pk_fma_f32 v[76:77], v[76:77], v[180:181], v[176:177]
	s_mov_b64 exec, s[100:101]
	global_store_dwordx4 v[94:95], v[76:79], off
	s_mov_b64 exec, -1
	s_nop 1
	s_nop 0
	v_pk_fma_f32 v[74:75], v[74:75], v[190:191], v[186:187]
	v_pk_fma_f32 v[72:73], v[72:73], v[188:189], v[184:185]
	s_mov_b64 exec, s[100:101]
	global_store_dwordx4 v[94:95], v[72:75], off offset:16
	s_mov_b64 exec, -1
	s_nop 1
	s_nop 0
	v_pk_fma_f32 v[70:71], v[70:71], v[198:199], v[194:195]
	v_pk_fma_f32 v[68:69], v[68:69], v[196:197], v[192:193]
	s_mov_b64 exec, s[100:101]
	global_store_dwordx4 v[94:95], v[68:71], off offset:512
	s_mov_b64 exec, -1
	s_nop 1
	v_add_u32_e32 v68, 0x80, v148
	v_cmp_gt_i32_e32 vcc, s33, v68
	v_cmp_lt_i32_e64 s[4:5], s42, v68
	s_nop 0
	v_pk_fma_f32 v[66:67], v[66:67], v[206:207], v[202:203]
	v_pk_fma_f32 v[64:65], v[64:65], v[204:205], v[200:201]
	s_mov_b64 exec, s[100:101]
	global_store_dwordx4 v[94:95], v[64:67], off offset:528
	s_mov_b64 exec, -1
	s_and_saveexec_b64 s[18:19], s[4:5]
	s_xor_b64 s[4:5], exec, s[18:19]
	v_lshlrev_b64 v[64:65], 13, v[128:129]
	v_mov_b32_e32 v69, v129
	v_lshl_add_u64 v[66:67], s[6:7], 0, v[64:65]
	v_lshlrev_b64 v[64:65], 13, v[68:69]
	s_andn2_saveexec_b64 s[4:5], s[4:5]
	v_ashrrev_i32_e32 v69, 31, v68
	v_lshlrev_b64 v[64:65], 13, v[68:69]
	v_lshl_add_u64 v[66:67], s[60:61], 0, v[64:65]
	s_or_b64 exec, exec, s[4:5]
	v_lshrrev_b32_e32 v68, 6, v128
	v_add_u32_e32 v68, 1, v68
	v_cndmask_b32_e64 v68, v68, 0, vcc
	v_lshl_add_u64 v[74:75], v[66:67], 0, v[146:147]
	v_mov_b64_e32 v[66:67], s[8:9]
	v_mad_u64_u32 v[66:67], s[4:5], v68, s41, v[66:67]
	v_lshl_add_u64 v[76:77], v[66:67], 0, v[146:147]
	global_load_dwordx4 v[176:179], v[74:75], off
	global_load_dwordx4 v[180:183], v[76:77], off
	global_load_dwordx4 v[184:187], v[74:75], off offset:16
	global_load_dwordx4 v[188:191], v[76:77], off offset:16
	global_load_dwordx4 v[192:195], v[74:75], off offset:512
	global_load_dwordx4 v[196:199], v[76:77], off offset:512
	global_load_dwordx4 v[200:203], v[74:75], off offset:528
	global_load_dwordx4 v[204:207], v[76:77], off offset:528
	v_lshl_add_u64 v[64:65], s[60:61], 0, v[64:65]
	v_lshl_add_u64 v[78:79], v[64:65], 0, v[146:147]
	v_add_u32_e32 v128, 0xffffc090, v148
	s_waitcnt vmcnt(0)
;     __device__ __forceinline__ void operator()(const f32x4 (&acc)[2][2][4][2], const pg8::Unit& u, int wr, int wc, int fr, int fq) const {
;         const int col0 = u.pn * 256 + wc * 32 + 8 * fq;
; #pragma unroll
;         for (int ai = 0; ai < 2; ++ai)
; #pragma unroll
;             for (int m = 0; m < 4; ++m) {
;                 const int row = u.pm * 256 + ai * 128 + wr * 64 + m * 16 + fr;
;                 const int b = row < TP ? 0 : 1 + ((row - TP) >> 6);
;                 const float* sp = (row < TP ? srcP + (size_t)row * DM : srcS + (size_t)(row - TP) * DM) + col0;
;                 const float* gp = gate + (size_t)b * MODW + col0; float* dp = dst + (size_t)row * DM + col0;
; #pragma unroll
;                 for (int bj = 0; bj < 2; ++bj)
; #pragma unroll
;                     for (int n = 0; n < 2; ++n) { const f32x4 x = *(const f32x4*)(sp + bj * 128 + 4 * n), gg = *(const f32x4*)(gp + bj * 128 + 4 * n);
;                         *(f32x4*)(dp + bj * 128 + 4 * n) = x + gg * acc[ai][bj][m][n]; }
	v_pk_fma_f32 v[62:63], v[62:63], v[182:183], v[178:179]
	v_pk_fma_f32 v[60:61], v[60:61], v[180:181], v[176:177]
	s_cmp_eq_u32 s98, 1
	s_cselect_b64 s[100:101], 0, -1
	s_mov_b64 exec, s[100:101]
	global_store_dwordx4 v[78:79], v[60:63], off
	s_mov_b64 exec, -1
	s_nop 1
	s_nop 0
	v_pk_fma_f32 v[58:59], v[58:59], v[190:191], v[186:187]
	v_pk_fma_f32 v[56:57], v[56:57], v[188:189], v[184:185]
	s_mov_b64 exec, s[100:101]
	global_store_dwordx4 v[78:79], v[56:59], off offset:16
	s_mov_b64 exec, -1
	s_nop 1
	s_nop 0
	v_pk_fma_f32 v[54:55], v[54:55], v[198:199], v[194:195]
	v_pk_fma_f32 v[52:53], v[52:53], v[196:197], v[192:193]
	s_mov_b64 exec, s[100:101]
	global_store_dwordx4 v[78:79], v[52:55], off offset:512
	s_mov_b64 exec, -1
	s_nop 1
	v_add_u32_e32 v52, 0x90, v148
	v_cmp_gt_i32_e32 vcc, s33, v52
	v_cmp_lt_i32_e64 s[4:5], s42, v52
	s_nop 0
	v_pk_fma_f32 v[50:51], v[50:51], v[206:207], v[202:203]
	v_pk_fma_f32 v[48:49], v[48:49], v[204:205], v[200:201]
	s_mov_b64 exec, s[100:101]
	global_store_dwordx4 v[78:79], v[48:51], off offset:528
	s_mov_b64 exec, -1
	s_and_saveexec_b64 s[18:19], s[4:5]
	s_xor_b64 s[4:5], exec, s[18:19]
	v_lshlrev_b64 v[48:49], 13, v[128:129]
	v_mov_b32_e32 v53, v129
	v_lshl_add_u64 v[50:51], s[6:7], 0, v[48:49]
	v_lshlrev_b64 v[48:49], 13, v[52:53]
	s_andn2_saveexec_b64 s[4:5], s[4:5]
	v_ashrrev_i32_e32 v53, 31, v52
	v_lshlrev_b64 v[48:49], 13, v[52:53]
	v_lshl_add_u64 v[50:51], s[60:61], 0, v[48:49]
	s_or_b64 exec, exec, s[4:5]
	v_lshrrev_b32_e32 v52, 6, v128
	v_add_u32_e32 v52, 1, v52
	v_cndmask_b32_e64 v52, v52, 0, vcc
	v_lshl_add_u64 v[58:59], v[50:51], 0, v[146:147]
	v_mov_b64_e32 v[50:51], s[8:9]
	v_mad_u64_u32 v[50:51], s[4:5], v52, s41, v[50:51]
	v_lshl_add_u64 v[60:61], v[50:51], 0, v[146:147]
	global_load_dwordx4 v[176:179], v[58:59], off
	global_load_dwordx4 v[180:183], v[60:61], off
	global_load_dwordx4 v[184:187], v[58:59], off offset:16
	global_load_dwordx4 v[188:191], v[60:61], off offset:16
	global_load_dwordx4 v[192:195], v[58:59], off offset:512
	global_load_dwordx4 v[196:199], v[60:61], off offset:512
	global_load_dwordx4 v[200:203], v[58:59], off offset:528
	global_load_dwordx4 v[204:207], v[60:61], off offset:528
	v_lshl_add_u64 v[48:49], s[60:61], 0, v[48:49]
	v_lshl_add_u64 v[62:63], v[48:49], 0, v[146:147]
	v_add_u32_e32 v128, 0xffffc0a0, v148
	s_waitcnt vmcnt(0)
	v_pk_fma_f32 v[46:47], v[46:47], v[182:183], v[178:179]
	v_pk_fma_f32 v[44:45], v[44:45], v[180:181], v[176:177]
	s_mov_b64 exec, s[100:101]
	global_store_dwordx4 v[62:63], v[44:47], off
	s_mov_b64 exec, -1
	s_nop 1
	s_nop 0
	v_pk_fma_f32 v[42:43], v[42:43], v[190:191], v[186:187]
	v_pk_fma_f32 v[40:41], v[40:41], v[188:189], v[184:185]
	s_mov_b64 exec, s[100:101]
	global_store_dwordx4 v[62:63], v[40:43], off offset:16
	s_mov_b64 exec, -1
	s_nop 1
	s_nop 0
	v_pk_fma_f32 v[38:39], v[38:39], v[198:199], v[194:195]
	v_pk_fma_f32 v[36:37], v[36:37], v[196:197], v[192:193]
	s_mov_b64 exec, s[100:101]
	global_store_dwordx4 v[62:63], v[36:39], off offset:512
	s_mov_b64 exec, -1
	s_nop 1
	v_add_u32_e32 v36, 0xa0, v148
	v_cmp_gt_i32_e32 vcc, s33, v36
	v_cmp_lt_i32_e64 s[4:5], s42, v36
	s_nop 0
	v_pk_fma_f32 v[34:35], v[34:35], v[206:207], v[202:203]
	v_pk_fma_f32 v[32:33], v[32:33], v[204:205], v[200:201]
	s_mov_b64 exec, s[100:101]
	global_store_dwordx4 v[62:63], v[32:35], off offset:528
	s_mov_b64 exec, -1
	s_and_saveexec_b64 s[18:19], s[4:5]
	s_xor_b64 s[4:5], exec, s[18:19]
	v_lshlrev_b64 v[32:33], 13, v[128:129]
	v_mov_b32_e32 v37, v129
	v_lshl_add_u64 v[34:35], s[6:7], 0, v[32:33]
	v_lshlrev_b64 v[32:33], 13, v[36:37]
	s_andn2_saveexec_b64 s[4:5], s[4:5]
	v_ashrrev_i32_e32 v37, 31, v36
	v_lshlrev_b64 v[32:33], 13, v[36:37]
	v_lshl_add_u64 v[34:35], s[60:61], 0, v[32:33]
	s_or_b64 exec, exec, s[4:5]
	v_lshrrev_b32_e32 v36, 6, v128
	v_add_u32_e32 v36, 1, v36
	v_cndmask_b32_e64 v36, v36, 0, vcc
	v_lshl_add_u64 v[42:43], v[34:35], 0, v[146:147]
	v_mov_b64_e32 v[34:35], s[8:9]
	v_mad_u64_u32 v[34:35], s[4:5], v36, s41, v[34:35]
	v_lshl_add_u64 v[44:45], v[34:35], 0, v[146:147]
	global_load_dwordx4 v[176:179], v[42:43], off
	global_load_dwordx4 v[180:183], v[44:45], off
	global_load_dwordx4 v[184:187], v[42:43], off offset:16
	global_load_dwordx4 v[188:191], v[44:45], off offset:16
	global_load_dwordx4 v[192:195], v[42:43], off offset:512
	global_load_dwordx4 v[196:199], v[44:45], off offset:512
	global_load_dwordx4 v[200:203], v[42:43], off offset:528
	global_load_dwordx4 v[204:207], v[44:45], off offset:528
	v_lshl_add_u64 v[32:33], s[60:61], 0, v[32:33]
	v_lshl_add_u64 v[46:47], v[32:33], 0, v[146:147]
	s_waitcnt vmcnt(0)
;     __device__ __forceinline__ void operator()(const f32x4 (&acc)[2][2][4][2], const pg8::Unit& u, int wr, int wc, int fr, int fq) const {
;         const int col0 = u.pn * 256 + wc * 32 + 8 * fq;
; #pragma unroll
;         for (int ai = 0; ai < 2; ++ai)
; #pragma unroll
;             for (int m = 0; m < 4; ++m) {
;                 const int row = u.pm * 256 + ai * 128 + wr * 64 + m * 16 + fr;
;                 const int b = row < TP ? 0 : 1 + ((row - TP) >> 6);
;                 const float* sp = (row < TP ? srcP + (size_t)row * DM : srcS + (size_t)(row - TP) * DM) + col0;
;                 const float* gp = gate + (size_t)b * MODW + col0; float* dp = dst + (size_t)row * DM + col0;
; #pragma unroll
;                 for (int bj = 0; bj < 2; ++bj)
; #pragma unroll
;                     for (int n = 0; n < 2; ++n) { const f32x4 x = *(const f32x4*)(sp + bj * 128 + 4 * n), gg = *(const f32x4*)(gp + bj * 128 + 4 * n);
;                         *(f32x4*)(dp + bj * 128 + 4 * n) = x + gg * acc[ai][bj][m][n]; }
	v_pk_fma_f32 v[30:31], v[30:31], v[182:183], v[178:179]
	v_pk_fma_f32 v[28:29], v[28:29], v[180:181], v[176:177]
	s_mov_b64 exec, s[100:101]
	global_store_dwordx4 v[46:47], v[28:31], off
	s_mov_b64 exec, -1
	s_nop 1
	s_nop 0
	v_pk_fma_f32 v[26:27], v[26:27], v[190:191], v[186:187]
	v_pk_fma_f32 v[24:25], v[24:25], v[188:189], v[184:185]
	s_mov_b64 exec, s[100:101]
	global_store_dwordx4 v[46:47], v[24:27], off offset:16
	s_mov_b64 exec, -1
	s_nop 1
	s_nop 0
	v_pk_fma_f32 v[22:23], v[22:23], v[198:199], v[194:195]
	v_pk_fma_f32 v[20:21], v[20:21], v[196:197], v[192:193]
	s_mov_b64 exec, s[100:101]
	global_store_dwordx4 v[46:47], v[20:23], off offset:512
	s_mov_b64 exec, -1
	s_nop 1
	v_add_u32_e32 v20, 0xb0, v148
	v_cmp_lt_i32_e32 vcc, s42, v20
	s_nop 0
	v_pk_fma_f32 v[18:19], v[18:19], v[206:207], v[202:203]
	v_pk_fma_f32 v[16:17], v[16:17], v[204:205], v[200:201]
	s_mov_b64 exec, s[100:101]
	global_store_dwordx4 v[46:47], v[16:19], off offset:528
	s_mov_b64 exec, -1
	s_and_saveexec_b64 s[4:5], vcc
	s_xor_b64 s[4:5], exec, s[4:5]
	v_add_u32_e32 v128, 0xffffc0b0, v148
	v_lshrrev_b32_e32 v16, 6, v128
	v_add_u32_e32 v22, 1, v16
	v_lshlrev_b64 v[16:17], 13, v[128:129]
	v_mov_b32_e32 v21, v129
	v_lshl_add_u64 v[18:19], s[6:7], 0, v[16:17]
	v_lshlrev_b64 v[16:17], 13, v[20:21]
	v_mad_u64_u32 v[22:23], s[18:19], v22, s41, 0
	s_andn2_saveexec_b64 s[4:5], s[4:5]
	v_ashrrev_i32_e32 v21, 31, v20
	v_lshlrev_b64 v[16:17], 13, v[20:21]
	v_lshl_add_u64 v[18:19], s[60:61], 0, v[16:17]
	v_mov_b64_e32 v[22:23], 0
	s_or_b64 exec, exec, s[4:5]
	v_lshl_add_u64 v[26:27], v[18:19], 0, v[146:147]
	v_lshl_add_u64 v[18:19], s[8:9], 0, v[22:23]
	v_lshl_add_u64 v[28:29], v[18:19], 0, v[146:147]
	global_load_dwordx4 v[176:179], v[26:27], off
	global_load_dwordx4 v[180:183], v[28:29], off
	global_load_dwordx4 v[184:187], v[26:27], off offset:16
	global_load_dwordx4 v[188:191], v[28:29], off offset:16
	global_load_dwordx4 v[192:195], v[26:27], off offset:512
	global_load_dwordx4 v[196:199], v[28:29], off offset:512
	global_load_dwordx4 v[200:203], v[26:27], off offset:528
	global_load_dwordx4 v[204:207], v[28:29], off offset:528
	v_lshl_add_u64 v[16:17], s[60:61], 0, v[16:17]
	v_lshl_add_u64 v[30:31], v[16:17], 0, v[146:147]
	s_and_b64 vcc, exec, s[0:1]
	s_mov_b64 s[0:1], -1
	s_waitcnt vmcnt(0)
	v_pk_fma_f32 v[14:15], v[14:15], v[182:183], v[178:179]
	v_pk_fma_f32 v[12:13], v[12:13], v[180:181], v[176:177]
	s_mov_b64 exec, s[100:101]
	global_store_dwordx4 v[30:31], v[12:15], off
	s_mov_b64 exec, -1
	s_nop 1
	s_nop 0
	v_pk_fma_f32 v[10:11], v[10:11], v[190:191], v[186:187]
	v_pk_fma_f32 v[8:9], v[8:9], v[188:189], v[184:185]
	s_mov_b64 exec, s[100:101]
	global_store_dwordx4 v[30:31], v[8:11], off offset:16
	s_mov_b64 exec, -1
	s_nop 1
	s_nop 0
	v_pk_fma_f32 v[6:7], v[6:7], v[198:199], v[194:195]
	v_pk_fma_f32 v[4:5], v[4:5], v[196:197], v[192:193]
	s_mov_b64 exec, s[100:101]
	global_store_dwordx4 v[30:31], v[4:7], off offset:512
	s_mov_b64 exec, -1
	s_nop 1
	s_nop 0
	v_pk_fma_f32 v[2:3], v[2:3], v[206:207], v[202:203]
	v_pk_fma_f32 v[0:1], v[0:1], v[204:205], v[200:201]
	s_mov_b64 exec, s[100:101]
	global_store_dwordx4 v[30:31], v[0:3], off offset:528
	s_mov_b64 exec, -1
	s_cbranch_vccnz .LBB0_2356
	s_andn2_b64 vcc, exec, s[2:3]
	s_cbranch_vccnz .LBB0_2355
	s_barrier
	s_branch .LBB0_2355
